# phase0 weight-transpose loop: 4 row loads + gain loads batched per tile; NSA selected-branch fast path hand-scheduled (QK(h1) under softmax(h0), PV(h0) under softmax(h1))
# baseline (speedup 1.0000x reference)
; DI bf16_t f2bf(float a) { return (bf16_t)(pack2(a, 0.f) & 0xffffu); }
; DI void phase0(const Params& p, const int L, bf16_t* lds) {
;     ...
;       const int nkt = K >> 6;
;       const int nt = t / nkt, kt = t - nt * nkt;
;       const int k0 = kt * 64, n0 = nt * 64;
;       __syncthreads();
;       {
;         const int c4 = tid & 15, n = n0 + c4 * 4;
; #pragma unroll
;         for (int i = 0; i < 4; ++i) {
;           const int k = (tid >> 4) + 16 * i;
;           float4 v = make_float4(0.f, 0.f, 0.f, 0.f);
;           if (n < N) v = *(const float4*)(W + (size_t)(k0 + k) * N + n);
;           if (gk) { const float g = gk[k0 + k]; v.x *= g; v.y *= g; v.z *= g; v.w *= g; }
;           T[(c4 * 4 + 0) * 66 + k] = f2bf(v.x);
;           T[(c4 * 4 + 1) * 66 + k] = f2bf(v.y);
;           T[(c4 * 4 + 2) * 66 + k] = f2bf(v.z);
;           T[(c4 * 4 + 3) * 66 + k] = f2bf(v.w);
;         }
;       }
.LBB0_44:
	s_lshr_b32 s28, s25, 6
	v_cvt_f32_u32_e32 v0, s28
	s_sub_i32 s56, 0, s28
	s_abs_i32 s39, s27
	s_ashr_i32 s38, s27, 31
	v_rcp_iflag_f32_e32 v0, v0
	s_barrier
	v_mul_f32_e32 v0, 0x4f7ffffe, v0
	v_cvt_u32_f32_e32 v0, v0
	s_nop 0
	v_readfirstlane_b32 s57, v0
	s_mul_i32 s56, s56, s57
	s_mul_hi_u32 s56, s57, s56
	s_add_i32 s57, s57, s56
	s_mul_hi_u32 s56, s39, s57
	s_mul_i32 s57, s56, s28
	s_sub_i32 s39, s39, s57
	s_add_i32 s58, s56, 1
	s_sub_i32 s57, s39, s28
	s_cmp_ge_u32 s39, s28
	s_cselect_b32 s56, s58, s56
	s_cselect_b32 s39, s57, s39
	s_add_i32 s57, s56, 1
	s_cmp_ge_u32 s39, s28
	s_cselect_b32 s39, s57, s56
	s_xor_b32 s39, s39, s38
	s_sub_i32 s38, s39, s38
	s_mul_i32 s39, s38, s28
	s_lshl_b32 s28, s38, 6
	s_sub_i32 s27, s27, s39
	v_or_b32_e32 v2, s28, v14
	s_lshl_b32 s56, s27, 6
	v_ashrrev_i32_e32 v3, 31, v2
	v_mov_b32_e32 v0, v1
	v_cmp_gt_i32_e64 s[38:39], s26, v2
	v_lshl_add_u64 v[10:11], v[2:3], 2, s[2:3]
	v_add_u32_e32 v12, s56, v6
	v_mov_b64_e32 v[26:27], v[0:1]
	v_mov_b64_e32 v[28:29], v[0:1]
	v_mov_b64_e32 v[30:31], v[0:1]
	v_mov_b64_e32 v[32:33], v[0:1]
	v_mov_b64_e32 v[34:35], v[0:1]
	v_mov_b64_e32 v[36:37], v[0:1]
	v_mov_b64_e32 v[38:39], v[0:1]
	v_mov_b64_e32 v[40:41], v[0:1]
	s_and_saveexec_b64 s[2:3], s[38:39]
	s_cbranch_execz .Lp0_a
	v_mad_u64_u32 v[44:45], s[60:61], v12, s26, 0
	v_lshl_add_u64 v[44:45], v[44:45], 2, v[10:11]
	global_load_dwordx4 v[26:29], v[44:45], off
	v_add_u32_e32 v42, s56, v19
	v_mad_u64_u32 v[44:45], s[60:61], v42, s26, 0
	v_lshl_add_u64 v[44:45], v[44:45], 2, v[10:11]
	global_load_dwordx4 v[30:33], v[44:45], off
	v_add_u32_e32 v42, s56, v20
	v_mad_u64_u32 v[44:45], s[60:61], v42, s26, 0
	v_lshl_add_u64 v[44:45], v[44:45], 2, v[10:11]
	global_load_dwordx4 v[34:37], v[44:45], off
	v_add_u32_e32 v42, s56, v21
	v_mad_u64_u32 v[44:45], s[60:61], v42, s26, 0
	v_lshl_add_u64 v[44:45], v[44:45], 2, v[10:11]
	global_load_dwordx4 v[38:41], v[44:45], off
.Lp0_a:
	s_or_b64 exec, exec, s[2:3]
	s_ashr_i32 s57, s56, 31
	s_cmp_eq_u64 s[54:55], 0
	s_cbranch_scc1 .Lp0_b
	v_lshl_add_u64 v[44:45], s[56:57], 0, v[6:7]
	v_lshl_add_u64 v[44:45], v[44:45], 2, s[54:55]
	global_load_dword v46, v[44:45], off
	global_load_dword v48, v[44:45], off offset:64
	global_load_dword v50, v[44:45], off offset:128
	global_load_dword v52, v[44:45], off offset:192
	s_waitcnt vmcnt(0)
	v_pk_mul_f32 v[26:27], v[26:27], v[46:47] op_sel_hi:[1,0]
	v_pk_mul_f32 v[28:29], v[28:29], v[46:47] op_sel_hi:[1,0]
	v_pk_mul_f32 v[30:31], v[30:31], v[48:49] op_sel_hi:[1,0]
	v_pk_mul_f32 v[32:33], v[32:33], v[48:49] op_sel_hi:[1,0]
	v_pk_mul_f32 v[34:35], v[34:35], v[50:51] op_sel_hi:[1,0]
	v_pk_mul_f32 v[36:37], v[36:37], v[50:51] op_sel_hi:[1,0]
	v_pk_mul_f32 v[38:39], v[38:39], v[52:53] op_sel_hi:[1,0]
	v_pk_mul_f32 v[40:41], v[40:41], v[52:53] op_sel_hi:[1,0]
.Lp0_b:
	s_waitcnt vmcnt(0)
	v_cvt_pk_bf16_f32 v0, v26, s0
	ds_write_b16 v17, v0
	v_cvt_pk_bf16_f32 v0, v27, s0
	ds_write_b16 v18, v0 offset:132
	v_cvt_pk_bf16_f32 v0, v28, s0
	ds_write_b16 v18, v0 offset:264
	v_cvt_pk_bf16_f32 v0, v29, s0
	ds_write_b16 v18, v0 offset:396
	v_cvt_pk_bf16_f32 v0, v30, s0
	ds_write_b16 v17, v0 offset:32
	v_cvt_pk_bf16_f32 v0, v31, s0
	ds_write_b16 v18, v0 offset:164
	v_cvt_pk_bf16_f32 v0, v32, s0
	ds_write_b16 v18, v0 offset:296
	v_cvt_pk_bf16_f32 v0, v33, s0
	ds_write_b16 v18, v0 offset:428
	v_cvt_pk_bf16_f32 v0, v34, s0
	ds_write_b16 v17, v0 offset:64
	v_cvt_pk_bf16_f32 v0, v35, s0
	ds_write_b16 v18, v0 offset:196
	v_cvt_pk_bf16_f32 v0, v36, s0
	ds_write_b16 v18, v0 offset:328
	v_cvt_pk_bf16_f32 v0, v37, s0
	ds_write_b16 v18, v0 offset:460
	v_mov_b32_e32 v12, v38
	v_mov_b32_e32 v13, v39
	v_mov_b32_e32 v10, v40
	v_mov_b32_e32 v11, v41
	s_branch .LBB0_8

; template <int MODE, bool FX>
; DI void attn_compute(const int lane, const bf16_t* Ks, const bf16_t* Vs, const bf16x8 (&qf)[2][2], AttnSt& st, const float (&invl)[2],
;                      int lo, int hi, float (&impA)[4], float (&impE)[4], const float CL) {
;     ...
;     constexpr float L2E = 1.4426950408889634f;
; #pragma unroll
;     for (int hh = 0; hh < 2; ++hh) {
;       float mL;
;       float il = 1.f;
;       if (FX) {
;         mL = full ? CL : 1e30f;
;         if (MODE == 1) il = invl[hh];
;       } else if (MODE != 1) {
;         float mx = -1e30f;
; #pragma unroll
;         for (int kt = 0; kt < 4; ++kt)
; #pragma unroll
;           for (int j = 0; j < 4; ++j) mx = fmaxf(mx, S[kt][hh][j]);
;         mx = full ? mx : -1e30f;
;         mx = fmaxf(mx, shx(mx, 16, lane));
;         mx = fmaxf(mx, shx(mx, 32, lane));
;         const float m_new = fmaxf(st.m[hh], mx);
;         const float alpha = __expf(st.m[hh] - m_new);
;         st.m[hh] = m_new;
;         st.l[hh] *= alpha;
;         if (MODE == 2) {
; #pragma unroll
;           for (int dt = 0; dt < 4; ++dt) st.O[hh][dt] *= alpha;
;         }
;         mL = full ? m_new * L2E : 1e30f;
;       } else {
;         mL = full ? st.m[hh] * L2E : 1e30f;
;         il = invl[hh];
;       }
;       float rs = 0.f;
; #pragma unroll
;       for (int kt = 0; kt < 4; ++kt) {
;         float a = 0.f;
; #pragma unroll
;         for (int j = 0; j < 4; ++j) {
;           float pv = __builtin_amdgcn_exp2f(fmaf(S[kt][hh][j], L2E, -mL));
;           if (MODE == 1) pv *= il;
;           S[kt][hh][j] = pv;
;           a += pv;
;         }
;         rs += a;
;         if (MODE == 1) {
;           impA[kt] += a;
;           impE[kt] += S[kt][hh][3];
;         }
;       }
;       if (MODE != 1 && !(FX && MODE == 2)) st.l[hh] += rs;
;       if (MODE != 0) {
; #pragma unroll
;         for (int c = 0; c < 2; ++c)
;           pf[hh][c] = mk8(pack2(S[2 * c][hh][0], S[2 * c][hh][1]), pack2(S[2 * c][hh][2], S[2 * c][hh][3]),
;                           pack2(S[2 * c + 1][hh][0], S[2 * c + 1][hh][1]), pack2(S[2 * c + 1][hh][2], S[2 * c + 1][hh][3]));
;       }
;     }
;     ...
;   if (MODE != 0) {
; #pragma unroll
;     for (int dt = 0; dt < 4; ++dt) {
;       const int row = dt * 16 + col;
;       const int sw = (row >> 1) & 7;
; #pragma unroll
;       for (int c = 0; c < 2; ++c) {
.Lnsa_fast:
	s_waitcnt lgkmcnt(7)
	v_mfma_f32_16x16x32_bf16 v[98:101], v[220:223], v[2:5], 0
	s_waitcnt lgkmcnt(6)
	v_mfma_f32_16x16x32_bf16 v[106:109], v[224:227], v[2:5], 0
	s_waitcnt lgkmcnt(5)
	v_mfma_f32_16x16x32_bf16 v[102:105], v[228:231], v[2:5], 0
	s_waitcnt lgkmcnt(4)
	v_mfma_f32_16x16x32_bf16 v[110:113], v[232:235], v[2:5], 0
	s_waitcnt lgkmcnt(3)
	v_mfma_f32_16x16x32_bf16 v[98:101], v[236:239], v[6:9], v[98:101]
	s_waitcnt lgkmcnt(2)
	v_mfma_f32_16x16x32_bf16 v[106:109], v[240:243], v[6:9], v[106:109]
	s_waitcnt lgkmcnt(1)
	v_mfma_f32_16x16x32_bf16 v[102:105], v[244:247], v[6:9], v[102:105]
	s_waitcnt lgkmcnt(0)
	v_mfma_f32_16x16x32_bf16 v[110:113], v[198:201], v[6:9], v[110:113]
	v_cmp_lt_i32_e32 vcc, 62, v215
	v_mfma_f32_16x16x32_bf16 v[90:93], v[220:223], v[10:13], 0
	v_mfma_f32_16x16x32_bf16 v[94:97], v[224:227], v[10:13], 0
	v_cndmask_b32_e32 v217, v197, v205, vcc
	v_mfma_f32_16x16x32_bf16 v[82:85], v[228:231], v[10:13], 0
	v_mfma_f32_16x16x32_bf16 v[86:89], v[232:235], v[10:13], 0
	v_fmamk_f32 v74, v98, 0x3fb8aa3b, v217
	v_fmamk_f32 v75, v99, 0x3fb8aa3b, v217
	v_mfma_f32_16x16x32_bf16 v[90:93], v[236:239], v[14:17], v[90:93]
	v_fmamk_f32 v76, v100, 0x3fb8aa3b, v217
	v_fmamk_f32 v77, v101, 0x3fb8aa3b, v217
	v_mfma_f32_16x16x32_bf16 v[94:97], v[240:243], v[14:17], v[94:97]
	v_fmamk_f32 v78, v106, 0x3fb8aa3b, v217
	v_fmamk_f32 v79, v107, 0x3fb8aa3b, v217
	v_mfma_f32_16x16x32_bf16 v[82:85], v[244:247], v[14:17], v[82:85]
	v_fmamk_f32 v80, v108, 0x3fb8aa3b, v217
	v_fmamk_f32 v81, v109, 0x3fb8aa3b, v217
	v_mfma_f32_16x16x32_bf16 v[86:89], v[198:201], v[14:17], v[86:89]
	ds_read_b64 v[220:221], v207 offset:8192
	v_fmamk_f32 v164, v102, 0x3fb8aa3b, v217
	ds_read_b64 v[222:223], v208 offset:8192
	v_fmamk_f32 v165, v103, 0x3fb8aa3b, v217
	ds_read_b64 v[224:225], v209 offset:8192
	v_fmamk_f32 v166, v104, 0x3fb8aa3b, v217
	ds_read_b64 v[226:227], v210 offset:8192
	v_fmamk_f32 v167, v105, 0x3fb8aa3b, v217
	ds_read_b64 v[228:229], v207 offset:10240
	v_fmamk_f32 v168, v110, 0x3fb8aa3b, v217
	ds_read_b64 v[230:231], v208 offset:10240
	v_fmamk_f32 v169, v111, 0x3fb8aa3b, v217
	ds_read_b64 v[232:233], v209 offset:10240
	v_fmamk_f32 v170, v112, 0x3fb8aa3b, v217
	ds_read_b64 v[234:235], v210 offset:10240
	v_fmamk_f32 v171, v113, 0x3fb8aa3b, v217
	ds_read_b64 v[236:237], v207 offset:12288
	v_exp_f32_e32 v74, v74
	ds_read_b64 v[238:239], v208 offset:12288
	v_exp_f32_e32 v75, v75
	ds_read_b64 v[240:241], v209 offset:12288
	v_exp_f32_e32 v76, v76
	ds_read_b64 v[242:243], v210 offset:12288
	v_exp_f32_e32 v77, v77
	ds_read_b64 v[244:245], v211 offset:8192
	v_exp_f32_e32 v78, v78
	ds_read_b64 v[246:247], v212 offset:8192
	v_exp_f32_e32 v79, v79
	ds_read_b64 v[198:199], v213 offset:8192
	v_exp_f32_e32 v80, v80
	ds_read_b64 v[200:201], v214 offset:8192
	v_exp_f32_e32 v81, v81
	v_exp_f32_e32 v164, v164
	v_exp_f32_e32 v165, v165
	v_exp_f32_e32 v166, v166
	v_exp_f32_e32 v167, v167
	v_exp_f32_e32 v168, v168
	v_exp_f32_e32 v169, v169
	v_exp_f32_e32 v170, v170
	v_exp_f32_e32 v171, v171
	v_cvt_pk_bf16_f32 v74, v74, v75
	v_cvt_pk_bf16_f32 v75, v76, v77
	v_cvt_pk_bf16_f32 v76, v78, v79
	v_cvt_pk_bf16_f32 v77, v80, v81
	v_cvt_pk_bf16_f32 v78, v164, v165
	v_cvt_pk_bf16_f32 v79, v166, v167
	v_cvt_pk_bf16_f32 v80, v168, v169
	v_cvt_pk_bf16_f32 v81, v170, v171
	s_waitcnt lgkmcnt(0)
	v_fmamk_f32 v164, v90, 0x3fb8aa3b, v217
	v_fmamk_f32 v165, v91, 0x3fb8aa3b, v217
	v_fmamk_f32 v166, v92, 0x3fb8aa3b, v217
	v_mfma_f32_16x16x32_bf16 v[50:53], v[220:223], v[74:77], v[50:53]
	v_fmamk_f32 v167, v93, 0x3fb8aa3b, v217
	s_mov_b32 s10, s8
	s_mov_b32 s11, s8
	s_mov_b32 s9, s8
	v_mfma_f32_16x16x32_bf16 v[42:45], v[228:231], v[74:77], v[42:45]
	v_mov_b64_e32 v[92:93], s[10:11]
	v_mov_b64_e32 v[90:91], s[8:9]
	v_fmamk_f32 v168, v94, 0x3fb8aa3b, v217
	v_fmamk_f32 v169, v95, 0x3fb8aa3b, v217
	v_mfma_f32_16x16x32_bf16 v[38:41], v[236:239], v[74:77], v[38:41]
	v_fmamk_f32 v170, v96, 0x3fb8aa3b, v217
	v_fmamk_f32 v171, v97, 0x3fb8aa3b, v217
	v_fmamk_f32 v172, v82, 0x3fb8aa3b, v217
	v_fmamk_f32 v173, v83, 0x3fb8aa3b, v217
	v_mfma_f32_16x16x32_bf16 v[34:37], v[244:247], v[74:77], v[34:37]
	v_fmamk_f32 v174, v84, 0x3fb8aa3b, v217
	v_fmamk_f32 v175, v85, 0x3fb8aa3b, v217
	v_fmamk_f32 v176, v86, 0x3fb8aa3b, v217
	v_fmamk_f32 v177, v87, 0x3fb8aa3b, v217
	v_mfma_f32_16x16x32_bf16 v[50:53], v[224:227], v[78:81], v[50:53]
	v_fmamk_f32 v178, v88, 0x3fb8aa3b, v217
	v_fmamk_f32 v179, v89, 0x3fb8aa3b, v217
	v_exp_f32_e32 v164, v164
	v_exp_f32_e32 v165, v165
	v_mfma_f32_16x16x32_bf16 v[42:45], v[232:235], v[78:81], v[42:45]
	v_exp_f32_e32 v166, v166
	v_exp_f32_e32 v167, v167
	v_exp_f32_e32 v168, v168
	v_exp_f32_e32 v169, v169
	v_mfma_f32_16x16x32_bf16 v[38:41], v[240:243], v[78:81], v[38:41]
	v_exp_f32_e32 v170, v170
	v_exp_f32_e32 v171, v171
	v_exp_f32_e32 v172, v172
	v_exp_f32_e32 v173, v173
	v_mfma_f32_16x16x32_bf16 v[34:37], v[198:201], v[78:81], v[34:37]
	v_exp_f32_e32 v174, v174
	v_exp_f32_e32 v175, v175
	v_exp_f32_e32 v176, v176
	v_exp_f32_e32 v177, v177
	v_mfma_f32_16x16x32_bf16 v[54:57], v[90:93], v[74:77], v[54:57]
	v_exp_f32_e32 v178, v178
	v_exp_f32_e32 v179, v179
	v_cvt_pk_bf16_f32 v82, v164, v165
	v_cvt_pk_bf16_f32 v83, v166, v167
	v_mfma_f32_16x16x32_bf16 v[54:57], v[90:93], v[78:81], v[54:57]
	v_cvt_pk_bf16_f32 v84, v168, v169
	v_cvt_pk_bf16_f32 v85, v170, v171
	v_cvt_pk_bf16_f32 v86, v172, v173
	v_cvt_pk_bf16_f32 v87, v174, v175
	v_cvt_pk_bf16_f32 v88, v176, v177
	v_cvt_pk_bf16_f32 v89, v178, v179
	s_nop 1
	v_mfma_f32_16x16x32_bf16 v[30:33], v[220:223], v[82:85], v[30:33]
	v_mfma_f32_16x16x32_bf16 v[26:29], v[228:231], v[82:85], v[26:29]
	v_mfma_f32_16x16x32_bf16 v[22:25], v[236:239], v[82:85], v[22:25]
	v_mfma_f32_16x16x32_bf16 v[18:21], v[244:247], v[82:85], v[18:21]
	v_mfma_f32_16x16x32_bf16 v[30:33], v[224:227], v[86:89], v[30:33]
	v_mfma_f32_16x16x32_bf16 v[26:29], v[232:235], v[86:89], v[26:29]
	v_mfma_f32_16x16x32_bf16 v[22:25], v[240:243], v[86:89], v[22:25]
	v_mfma_f32_16x16x32_bf16 v[18:21], v[198:201], v[86:89], v[18:21]
	v_mfma_f32_16x16x32_bf16 v[46:49], v[90:93], v[82:85], v[46:49]
	v_mfma_f32_16x16x32_bf16 v[46:49], v[90:93], v[86:89], v[46:49]
	s_branch .LBB0_667

; DI f32x4 mfma16(bf16x8 a, bf16x8 b, f32x4 c) { return __builtin_amdgcn_mfma_f32_16x16x32_bf16(a, b, c, 0, 0, 0); }
; template <int MODE, bool FX>
; DI void attn_compute(const int lane, const bf16_t* Ks, const bf16_t* Vs, const bf16x8 (&qf)[2][2], AttnSt& st, const float (&invl)[2],
;                      int lo, int hi, float (&impA)[4], float (&impE)[4], const float CL) {
;     ...
;   for (int ks = 0; ks < 2; ++ks) {
; #pragma unroll
;     for (int kt = 0; kt < 4; ++kt) {
;       int row = kt * 16 + col;
;       bf16x8 kf = *(const bf16x8*)(Ks + row * 64 + (((ks * 4 + quad) ^ ((row >> 1) & 7)) << 3));
; #pragma unroll
;       for (int hh = 0; hh < 2; ++hh) S[kt][hh] = mfma16(kf, qf[hh][ks], S[kt][hh]);
;     }
;   }
;   bf16x8 pf[2][2];
;   const bool full = (lo <= 0) && (hi >= 63);
;   const bool none = (hi < 0) || (lo > 63) || (hi < lo);
;   if (__all(full || none)) {
; template <bool FX>
; DI void nsa_tile(const Params& p, int b, int g, int tile, bf16_t* lds, const float CL) {
;     ...
;         uint32_t wsel = (s < 32) ? sw0 : (s < 64) ? sw1 : (s < 96) ? sw2 : sw3;
;         bool sel = (wsel >> (s & 31)) & 1u;
;         int hi = sel ? (tok - s * 64) : -1;
;         if (__any(hi >= 0)) attn_compute<2, FX>(lane, Ks, Vs, qf, st, invl, 0, hi, dA, dE, CL);
.LBB0_670:
	s_cmp_lt_u32 s68, 32
	s_cselect_b64 vcc, -1, 0
	s_cmp_lt_u32 s68, 64
	s_cselect_b64 s[2:3], -1, 0
	s_cmpk_lt_u32 s68, 0x60
	s_cselect_b64 s[4:5], -1, 0
	v_cndmask_b32_e64 v74, v183, v182, s[4:5]
	v_cndmask_b32_e64 v74, v74, v181, s[2:3]
	v_cndmask_b32_e32 v74, v74, v180, vcc
	v_lshrrev_b32_e32 v74, s68, v74
	v_and_b32_e32 v74, 1, v74
	v_cmp_eq_u32_e32 vcc, 1, v74
	s_nop 1
	v_cndmask_b32_e32 v215, -1, v187, vcc
	v_cmp_lt_i32_e32 vcc, -1, v215
	s_cbranch_vccz .LBB0_667
	ds_read_b128 v[220:223], v188
	ds_read_b128 v[224:227], v188 offset:2048
	ds_read_b128 v[228:231], v188 offset:4096
	ds_read_b128 v[232:235], v189
	ds_read_b128 v[236:239], v190
	ds_read_b128 v[240:243], v190 offset:2048
	ds_read_b128 v[244:247], v190 offset:4096
	ds_read_b128 v[198:201], v191
	v_cmp_lt_u32_e32 vcc, 62, v215
	s_mov_b64 s[2:3], -1
	s_cmp_eq_u64 vcc, exec
	s_cbranch_scc1 .Lnsa_fast
	s_waitcnt lgkmcnt(7)
	v_mfma_f32_16x16x32_bf16 v[98:101], v[220:223], v[2:5], 0
	v_mfma_f32_16x16x32_bf16 v[90:93], v[220:223], v[10:13], 0
	s_waitcnt lgkmcnt(6)
	v_mfma_f32_16x16x32_bf16 v[106:109], v[224:227], v[2:5], 0
	v_mfma_f32_16x16x32_bf16 v[94:97], v[224:227], v[10:13], 0
	s_waitcnt lgkmcnt(5)
	v_mfma_f32_16x16x32_bf16 v[102:105], v[228:231], v[2:5], 0
	v_mfma_f32_16x16x32_bf16 v[82:85], v[228:231], v[10:13], 0
	s_waitcnt lgkmcnt(4)
	v_mfma_f32_16x16x32_bf16 v[110:113], v[232:235], v[2:5], 0
	v_mfma_f32_16x16x32_bf16 v[86:89], v[232:235], v[10:13], 0
	s_waitcnt lgkmcnt(3)
	v_mfma_f32_16x16x32_bf16 v[98:101], v[236:239], v[6:9], v[98:101]
	v_mfma_f32_16x16x32_bf16 v[90:93], v[236:239], v[14:17], v[90:93]
	s_waitcnt lgkmcnt(2)
	v_mfma_f32_16x16x32_bf16 v[106:109], v[240:243], v[6:9], v[106:109]
	v_mfma_f32_16x16x32_bf16 v[94:97], v[240:243], v[14:17], v[94:97]
	s_waitcnt lgkmcnt(1)
	v_mfma_f32_16x16x32_bf16 v[102:105], v[244:247], v[6:9], v[102:105]
	v_mfma_f32_16x16x32_bf16 v[82:85], v[244:247], v[14:17], v[82:85]
	s_waitcnt lgkmcnt(0)
	v_mfma_f32_16x16x32_bf16 v[110:113], v[198:201], v[6:9], v[110:113]
	v_mfma_f32_16x16x32_bf16 v[86:89], v[198:201], v[14:17], v[86:89]
	ds_read_b64 v[220:221], v207 offset:8192
	ds_read_b64 v[222:223], v208 offset:8192
	ds_read_b64 v[224:225], v209 offset:8192
	ds_read_b64 v[226:227], v210 offset:8192
	ds_read_b64 v[228:229], v207 offset:10240
	ds_read_b64 v[230:231], v208 offset:10240
	ds_read_b64 v[232:233], v209 offset:10240
	ds_read_b64 v[234:235], v210 offset:10240
	ds_read_b64 v[236:237], v207 offset:12288
	ds_read_b64 v[238:239], v208 offset:12288
	ds_read_b64 v[240:241], v209 offset:12288
	ds_read_b64 v[242:243], v210 offset:12288
	ds_read_b64 v[244:245], v211 offset:8192
	ds_read_b64 v[246:247], v212 offset:8192
	ds_read_b64 v[198:199], v213 offset:8192
	ds_read_b64 v[200:201], v214 offset:8192
	s_cbranch_scc1 .LBB0_673
; template <int MODE, bool FX>
; DI void attn_compute(const int lane, const bf16_t* Ks, const bf16_t* Vs, const bf16x8 (&qf)[2][2], AttnSt& st, const float (&invl)[2],
;                      int lo, int hi, float (&impA)[4], float (&impE)[4], const float CL) {
;     ...
;     if (FX) {
;       constexpr float L2E = 1.4426950408889634f;
;       const float il = (MODE == 1) ? invl[hh] : 1.f;
;       float rs = 0.f;
; #pragma unroll
;       for (int kt = 0; kt < 4; ++kt) {
;         float a = 0.f;
; #pragma unroll
;         for (int j = 0; j < 4; ++j) {
;           const int kl = kt * 16 + quad * 4 + j;
;           const bool v = (kl >= lo) && (kl <= hi);
;           float pv = v ? __builtin_amdgcn_exp2f(fmaf(S[kt][hh][j], L2E, -CL)) : 0.f;
;           if (MODE == 1) pv *= il;
;           S[kt][hh][j] = pv;
;           a += pv;
;         }
;         rs += a;
;         if (MODE == 1) {
;           impA[kt] += a;
;           impE[kt] += S[kt][hh][3];
;         }
;       }
;       if (MODE != 1 && !(FX && MODE == 2)) st.l[hh] += rs;
;       if (MODE != 0) {
; #pragma unroll
;         for (int c = 0; c < 2; ++c)
;           pf[hh][c] = mk8(pack2(S[2 * c][hh][0], S[2 * c][hh][1]), pack2(S[2 * c][hh][2], S[2 * c][hh][3]),
;                           pack2(S[2 * c + 1][hh][0], S[2 * c + 1][hh][1]), pack2(S[2 * c + 1][hh][2], S[2 * c + 1][hh][3]));
;       }
	v_fmamk_f32 v74, v98, 0x3fb8aa3b, v205
	v_fmamk_f32 v75, v99, 0x3fb8aa3b, v205
	v_fmamk_f32 v76, v100, 0x3fb8aa3b, v205
	v_fmamk_f32 v77, v101, 0x3fb8aa3b, v205
	v_fmamk_f32 v78, v106, 0x3fb8aa3b, v205
	v_fmamk_f32 v79, v107, 0x3fb8aa3b, v205
	v_fmamk_f32 v80, v108, 0x3fb8aa3b, v205
	v_fmamk_f32 v81, v109, 0x3fb8aa3b, v205
	v_fmamk_f32 v164, v102, 0x3fb8aa3b, v205
	v_fmamk_f32 v165, v103, 0x3fb8aa3b, v205
	v_fmamk_f32 v166, v104, 0x3fb8aa3b, v205
	v_fmamk_f32 v167, v105, 0x3fb8aa3b, v205
	v_fmamk_f32 v168, v110, 0x3fb8aa3b, v205
	v_fmamk_f32 v169, v111, 0x3fb8aa3b, v205
	v_fmamk_f32 v170, v112, 0x3fb8aa3b, v205
	v_fmamk_f32 v171, v113, 0x3fb8aa3b, v205
	v_exp_f32_e32 v74, v74
	v_exp_f32_e32 v75, v75
	v_exp_f32_e32 v76, v76
	v_exp_f32_e32 v77, v77
	v_exp_f32_e32 v78, v78
	v_exp_f32_e32 v79, v79
	v_exp_f32_e32 v80, v80
	v_exp_f32_e32 v81, v81
	v_exp_f32_e32 v164, v164
	v_exp_f32_e32 v165, v165
	v_exp_f32_e32 v166, v166
	v_exp_f32_e32 v167, v167
	v_exp_f32_e32 v168, v168
	v_exp_f32_e32 v169, v169
	v_exp_f32_e32 v170, v170
	v_exp_f32_e32 v171, v171
	v_cmp_gt_i32_e32 vcc, v118, v215
	v_cmp_lt_i32_e64 s[2:3], v118, v215
	v_cmp_gt_i32_e64 s[52:53], v119, v215
	v_cmp_gt_i32_e64 s[54:55], v192, v215
	v_cmp_gt_i32_e64 s[40:41], v120, v215
	v_cmp_gt_i32_e64 s[42:43], v193, v215
	v_cmp_gt_i32_e64 s[56:57], v122, v215
	v_cmp_gt_i32_e64 s[58:59], v121, v215
	v_cmp_gt_i32_e64 s[44:45], v194, v215
	v_cmp_gt_i32_e64 s[46:47], v195, v215
	v_cmp_gt_i32_e64 s[60:61], v206, v215
	v_cmp_gt_i32_e64 s[62:63], v124, v215
	v_cmp_gt_i32_e64 s[48:49], v126, v215
	v_cmp_gt_i32_e64 s[50:51], v123, v215
	v_cmp_gt_i32_e64 s[64:65], v125, v215
	v_cmp_gt_i32_e64 s[66:67], v127, v215
	v_cndmask_b32_e64 v74, v74, 0, vcc
	v_cndmask_b32_e64 v75, 0, v75, s[2:3]
	v_cndmask_b32_e64 v76, v76, 0, s[52:53]
	v_cndmask_b32_e64 v77, v77, 0, s[54:55]
	v_cndmask_b32_e64 v78, v78, 0, s[40:41]
	v_cndmask_b32_e64 v79, v79, 0, s[42:43]
	v_cndmask_b32_e64 v80, v80, 0, s[56:57]
	v_cndmask_b32_e64 v81, v81, 0, s[58:59]
	v_cndmask_b32_e64 v164, v164, 0, s[44:45]
	v_cndmask_b32_e64 v165, v165, 0, s[46:47]
	v_cndmask_b32_e64 v166, v166, 0, s[60:61]
	v_cndmask_b32_e64 v167, v167, 0, s[62:63]
	v_cndmask_b32_e64 v168, v168, 0, s[48:49]
	v_cndmask_b32_e64 v169, v169, 0, s[50:51]
	v_cndmask_b32_e64 v170, v170, 0, s[64:65]
	v_cndmask_b32_e64 v171, v171, 0, s[66:67]
	v_cvt_pk_bf16_f32 v74, v74, v75
	v_cvt_pk_bf16_f32 v75, v76, v77
	v_cvt_pk_bf16_f32 v76, v78, v79
	v_cvt_pk_bf16_f32 v77, v80, v81
	v_cvt_pk_bf16_f32 v78, v164, v165
	v_cvt_pk_bf16_f32 v79, v166, v167
	v_cvt_pk_bf16_f32 v80, v168, v169
	v_cvt_pk_bf16_f32 v81, v170, v171
	v_fmamk_f32 v164, v90, 0x3fb8aa3b, v205
	v_fmamk_f32 v165, v91, 0x3fb8aa3b, v205
	v_fmamk_f32 v166, v92, 0x3fb8aa3b, v205
	v_fmamk_f32 v167, v93, 0x3fb8aa3b, v205
	v_fmamk_f32 v168, v94, 0x3fb8aa3b, v205
	v_fmamk_f32 v169, v95, 0x3fb8aa3b, v205
	v_fmamk_f32 v170, v96, 0x3fb8aa3b, v205
	v_fmamk_f32 v171, v97, 0x3fb8aa3b, v205
	v_fmamk_f32 v172, v82, 0x3fb8aa3b, v205
	v_fmamk_f32 v173, v83, 0x3fb8aa3b, v205
	v_fmamk_f32 v174, v84, 0x3fb8aa3b, v205
	v_fmamk_f32 v175, v85, 0x3fb8aa3b, v205
	v_fmamk_f32 v176, v86, 0x3fb8aa3b, v205
	v_fmamk_f32 v177, v87, 0x3fb8aa3b, v205
	v_fmamk_f32 v178, v88, 0x3fb8aa3b, v205
	v_fmamk_f32 v179, v89, 0x3fb8aa3b, v205
	v_exp_f32_e32 v164, v164
	v_exp_f32_e32 v165, v165
	v_exp_f32_e32 v166, v166
	v_exp_f32_e32 v167, v167
	v_exp_f32_e32 v168, v168
	v_exp_f32_e32 v169, v169
	v_exp_f32_e32 v170, v170
	v_exp_f32_e32 v171, v171
	v_exp_f32_e32 v172, v172
	v_exp_f32_e32 v173, v173
	v_exp_f32_e32 v174, v174
	v_exp_f32_e32 v175, v175
	v_exp_f32_e32 v176, v176
	v_exp_f32_e32 v177, v177
	v_exp_f32_e32 v178, v178
	v_exp_f32_e32 v179, v179
	v_cndmask_b32_e64 v164, v164, 0, vcc
	v_cndmask_b32_e64 v165, 0, v165, s[2:3]
	v_cndmask_b32_e64 v166, v166, 0, s[52:53]
	v_cndmask_b32_e64 v167, v167, 0, s[54:55]
	v_cndmask_b32_e64 v168, v168, 0, s[40:41]
	v_cndmask_b32_e64 v169, v169, 0, s[42:43]
	v_cndmask_b32_e64 v170, v170, 0, s[56:57]
	v_cndmask_b32_e64 v171, v171, 0, s[58:59]
	v_cndmask_b32_e64 v172, v172, 0, s[44:45]
	v_cndmask_b32_e64 v173, v173, 0, s[46:47]
	v_cndmask_b32_e64 v174, v174, 0, s[60:61]
	v_cndmask_b32_e64 v175, v175, 0, s[62:63]
	v_cndmask_b32_e64 v176, v176, 0, s[48:49]
	v_cndmask_b32_e64 v177, v177, 0, s[50:51]
	v_cndmask_b32_e64 v178, v178, 0, s[64:65]
	v_cndmask_b32_e64 v179, v179, 0, s[66:67]
	s_mov_b64 s[2:3], 0
